# seams 2/4/5: waves 1..7 touch the next GEMM phase's first two K-tiles (W_out / W_down + HID / W_ple_gate) while wave 0 polls
# baseline (speedup 1.0000x reference)
; __device__ __forceinline__ unsigned xb_add(unsigned* p, unsigned v) { return __hip_atomic_fetch_add(p, v, __ATOMIC_RELAXED, __HIP_MEMORY_SCOPE_AGENT); }
; __device__ __forceinline__ void grp_barrier(unsigned* cntw, unsigned* tmo) {
;     asm volatile("s_waitcnt vmcnt(0)" ::: "memory");
;     __syncthreads();
;     if (threadIdx.x == 0) {
;         __builtin_amdgcn_s_waitcnt(0);
;         asm volatile("buffer_inv sc1" ::: "memory");
;         const unsigned old = xb_add(cntw, 1u);
;         const unsigned target = (old / 32u + 1u) * 32u;
.LBB0_659:
	s_cmp_gt_i32 s77, 3
	s_cselect_b64 s[2:3], -1, 0
	s_and_b64 s[0:1], s[24:25], s[2:3]
	s_andn2_b64 vcc, exec, s[0:1]
	s_cbranch_vccnz .LBB0_729
	s_add_i32 s0, 0, 0x20170
	v_mov_b32_e32 v1, s0
	ds_read_b32 v1, v1
	s_waitcnt lgkmcnt(0)
	v_cmp_eq_u32_e32 vcc, 0, v1
	s_cbranch_vccnz .LBB0_673
	s_waitcnt vmcnt(0)
	s_barrier
	v_readfirstlane_b32 s98, v0
	s_cmp_lt_u32 s98, 64
	s_cbranch_scc1 .Lwarm_s2_skip
	v_add_u32_e32 v250, 0xffffffc0, v0
	v_add_u32_e32 v251, 0x1c0, v250
	v_and_b32_e32 v251, 0x1ff, v251
	s_lshr_b32 s100, s10, 6
	s_mul_i32 s100, s100, 0x80000
	s_add_u32 s98, s22, 0x600000
	s_addc_u32 s99, s23, 0
	s_add_u32 s98, s98, s100
	s_addc_u32 s99, s99, 0
	s_movk_i32 s101, 0x800
	v_lshrrev_b32_e32 v252, 1, v250
	v_and_b32_e32 v253, 1, v250
	v_lshlrev_b32_e32 v253, 7, v253
	v_mad_u32_u24 v252, v252, s101, v253
	global_load_dword v249, v252, s[98:99]
	v_lshrrev_b32_e32 v252, 1, v251
	v_and_b32_e32 v253, 1, v251
	v_lshlrev_b32_e32 v253, 7, v253
	v_mad_u32_u24 v252, v252, s101, v253
	global_load_dword v249, v252, s[98:99]
.Lwarm_s2_skip:
	s_and_saveexec_b64 s[0:1], s[92:93]
	s_cbranch_execz .LBB0_678
	s_lshl_b32 s4, s10, 8
	s_and_b32 s4, s4, 0x700
	s_mov_b64 s[6:7], exec
	s_add_u32 s4, s22, s4
	s_addc_u32 s5, s23, 0
	s_waitcnt vmcnt(0) expcnt(0) lgkmcnt(0)
	buffer_inv sc1
	v_mbcnt_lo_u32_b32 v1, s6, 0
	s_add_u32 s4, s4, 0x2800
	v_mbcnt_hi_u32_b32 v2, s7, v1
	s_addc_u32 s5, s5, 0
	v_cmp_eq_u32_e32 vcc, 0, v2
	s_and_saveexec_b64 s[8:9], vcc
	s_cbranch_execz .LBB0_664
	s_bcnt1_i32_b64 s6, s[6:7]
	v_mov_b32_e32 v1, 0
	v_mov_b32_e32 v3, s6
	global_atomic_add v3, v1, v3, s[4:5] sc0

; __device__ __forceinline__ unsigned xb_add(unsigned* p, unsigned v) { return __hip_atomic_fetch_add(p, v, __ATOMIC_RELAXED, __HIP_MEMORY_SCOPE_AGENT); }
; __device__ __forceinline__ void grp_barrier(unsigned* cntw, unsigned* tmo) {
;     asm volatile("s_waitcnt vmcnt(0)" ::: "memory");
;     __syncthreads();
;     if (threadIdx.x == 0) {
;         __builtin_amdgcn_s_waitcnt(0);
;         asm volatile("buffer_inv sc1" ::: "memory");
;         const unsigned old = xb_add(cntw, 1u);
;         const unsigned target = (old / 32u + 1u) * 32u;
.LBB0_894:
	s_cmp_gt_i32 s77, 5
	s_cselect_b64 s[0:1], -1, 0
	s_and_b64 s[2:3], s[16:17], s[0:1]
	s_andn2_b64 vcc, exec, s[2:3]
	s_cbranch_vccnz .LBB0_964
	s_add_i32 s2, 0, 0x20170
	v_mov_b32_e32 v1, s2
	ds_read_b32 v1, v1
	s_waitcnt lgkmcnt(0)
	v_cmp_eq_u32_e32 vcc, 0, v1
	s_cbranch_vccnz .LBB0_908
	s_waitcnt vmcnt(0)
	s_barrier
	v_readfirstlane_b32 s98, v0
	s_cmp_lt_u32 s98, 64
	s_cbranch_scc1 .Lwarm_s4_skip
	v_add_u32_e32 v250, 0xffffffc0, v0
	v_add_u32_e32 v251, 0x1c0, v250
	v_and_b32_e32 v251, 0x1ff, v251
	s_lshr_b32 s100, s10, 6
	s_mul_i32 s100, s100, 0x160000
	s_add_u32 s98, s22, 0x1300000
	s_addc_u32 s99, s23, 0
	s_add_u32 s98, s98, s100
	s_addc_u32 s99, s99, 0
	s_movk_i32 s101, 0x1600
	v_lshrrev_b32_e32 v252, 1, v250
	v_and_b32_e32 v253, 1, v250
	v_lshlrev_b32_e32 v253, 7, v253
	v_mad_u32_u24 v252, v252, s101, v253
	global_load_dword v249, v252, s[98:99]
	v_lshrrev_b32_e32 v252, 1, v251
	v_and_b32_e32 v253, 1, v251
	v_lshlrev_b32_e32 v253, 7, v253
	v_mad_u32_u24 v252, v252, s101, v253
	global_load_dword v249, v252, s[98:99]
	s_and_b32 s100, s10, 7
	s_lshl_b32 s100, s100, 3
	s_bfe_u32 s101, s10, 0x30003
	s_add_i32 s100, s100, s101
	s_mul_i32 s100, s100, 0x160000
	s_add_u32 s98, s22, 0x5d00000
	s_addc_u32 s99, s23, 0
	s_add_u32 s98, s98, s100
	s_addc_u32 s99, s99, 0
	s_movk_i32 s101, 0x1600
	v_lshrrev_b32_e32 v252, 1, v250
	v_and_b32_e32 v253, 1, v250
	v_lshlrev_b32_e32 v253, 7, v253
	v_mad_u32_u24 v252, v252, s101, v253
	global_load_dword v249, v252, s[98:99]
	v_lshrrev_b32_e32 v252, 1, v251
	v_and_b32_e32 v253, 1, v251
	v_lshlrev_b32_e32 v253, 7, v253
	v_mad_u32_u24 v252, v252, s101, v253
	global_load_dword v249, v252, s[98:99]
.Lwarm_s4_skip:
	s_and_saveexec_b64 s[2:3], s[92:93]
	s_cbranch_execz .LBB0_913
	s_lshl_b32 s4, s10, 8
	s_and_b32 s4, s4, 0x700
	s_mov_b64 s[6:7], exec
	s_add_u32 s4, s22, s4
	s_addc_u32 s5, s23, 0
	s_waitcnt vmcnt(0) expcnt(0) lgkmcnt(0)
	buffer_inv sc1
	v_mbcnt_lo_u32_b32 v1, s6, 0
	s_add_u32 s4, s4, 0x2800
	v_mbcnt_hi_u32_b32 v2, s7, v1
	s_addc_u32 s5, s5, 0
	v_cmp_eq_u32_e32 vcc, 0, v2
	s_and_saveexec_b64 s[8:9], vcc
	s_cbranch_execz .LBB0_899
	s_bcnt1_i32_b64 s6, s[6:7]
	v_mov_b32_e32 v1, 0
	v_mov_b32_e32 v3, s6
	global_atomic_add v3, v1, v3, s[4:5] sc0

; __device__ __forceinline__ void grp_barrier(unsigned* cntw, unsigned* tmo) {
;     asm volatile("s_waitcnt vmcnt(0)" ::: "memory");
;     __syncthreads();
.LBB0_1021:
	s_cmp_gt_i32 s77, 6
	s_cselect_b64 s[2:3], -1, 0
	s_and_b64 s[0:1], s[0:1], s[2:3]
	s_andn2_b64 vcc, exec, s[0:1]
	s_cbranch_vccnz .LBB0_1091
	s_add_i32 s0, 0, 0x20170
	v_mov_b32_e32 v1, s0
	ds_read_b32 v1, v1
	s_waitcnt lgkmcnt(0)
	v_cmp_eq_u32_e32 vcc, 0, v1
	s_cbranch_vccnz .LBB0_1035
	s_waitcnt vmcnt(0)
	s_barrier
	v_readfirstlane_b32 s98, v0
	s_cmp_lt_u32 s98, 64
	s_cbranch_scc1 .Lwarm_s5_skip
	v_add_u32_e32 v250, 0xffffffc0, v0
	v_add_u32_e32 v251, 0x1c0, v250
	v_and_b32_e32 v251, 0x1ff, v251
	s_lshr_b32 s100, s10, 6
	s_mul_i32 s100, s100, 0x80000
	s_add_u32 s98, s22, 0x1900000
	s_addc_u32 s99, s23, 0
	s_add_u32 s98, s98, s100
	s_addc_u32 s99, s99, 0
	s_movk_i32 s101, 0x800
	v_lshrrev_b32_e32 v252, 1, v250
	v_and_b32_e32 v253, 1, v250
	v_lshlrev_b32_e32 v253, 7, v253
	v_mad_u32_u24 v252, v252, s101, v253
	global_load_dword v249, v252, s[98:99]
	v_lshrrev_b32_e32 v252, 1, v251
	v_and_b32_e32 v253, 1, v251
	v_lshlrev_b32_e32 v253, 7, v253
	v_mad_u32_u24 v252, v252, s101, v253
	global_load_dword v249, v252, s[98:99]
